# attention row sums with packed v_pk_add_f32 (28 fewer VALU ops per key tile per wave)
# baseline (speedup 1.0000x reference)
; #define LAS __attribute__((address_space(3)))
; __device__ __forceinline__ void attn_unit2(LAS unsigned char* lds, const bf16_t* __restrict__ Q, const bf16_t* __restrict__ KN, const bf16_t* __restrict__ KPE, ...
;     ...
;         for (int ds = 0; ds < 6; ++ds) {
;             const bf16x8 k0 = *(const LAS bf16x8*)(ka + ds * 32);
;             const bf16x8 k1 = *(const LAS bf16x8*)(ka + 32 * KROW + ds * 32);
;             sa0 = __builtin_amdgcn_mfma_f32_32x32x16_bf16(k0, qa[ds], sa0, 0, 0, 0);
;             sa1 = __builtin_amdgcn_mfma_f32_32x32x16_bf16(k1, qa[ds], sa1, 0, 0, 0);
;             sb0 = __builtin_amdgcn_mfma_f32_32x32x16_bf16(k0, qb[ds], sb0, 0, 0, 0);
;             sb1 = __builtin_amdgcn_mfma_f32_32x32x16_bf16(k1, qb[ds], sb1, 0, 0, 0);
;         }
.Lat_back_aE:
	v_exp_f32_e32 v64, v64
	v_mfma_f32_32x32x16_bf16 v[32:47], v[196:199], v[112:115], v[32:47]
	v_exp_f32_e32 v65, v65
	v_exp_f32_e32 v66, v66
	v_exp_f32_e32 v67, v67
	v_exp_f32_e32 v68, v68
	v_mfma_f32_32x32x16_bf16 v[0:15], v[200:203], v[112:115], v[0:15]
	v_exp_f32_e32 v69, v69
	v_pk_add_f32 v[230:231], v[64:65], v[66:67]
	v_exp_f32_e32 v70, v70
	v_exp_f32_e32 v71, v71
	v_mfma_f32_32x32x16_bf16 v[32:47], v[204:207], v[116:119], v[32:47]
	v_pk_add_f32 v[230:231], v[230:231], v[68:69]
	v_exp_f32_e32 v72, v72
	v_exp_f32_e32 v73, v73
	v_pk_add_f32 v[230:231], v[230:231], v[70:71]
	v_mfma_f32_32x32x16_bf16 v[0:15], v[208:211], v[116:119], v[0:15]
	v_exp_f32_e32 v74, v74
	v_add3_u32 v225, s34, v187, v128
	ds_read_b128 v[196:199], v225 offset:13312
	ds_read_b128 v[200:203], v225 offset:17920
	ds_read_b128 v[204:207], v225 offset:13344
	ds_read_b128 v[208:211], v225 offset:17952
	v_exp_f32_e32 v75, v75
	v_pk_add_f32 v[230:231], v[230:231], v[72:73]
	v_exp_f32_e32 v76, v76
	v_mfma_f32_32x32x16_bf16 v[96:111], v[240:243], v[244:247], 0
	v_exp_f32_e32 v77, v77
	v_pk_add_f32 v[230:231], v[230:231], v[74:75]
	v_exp_f32_e32 v78, v78
	v_exp_f32_e32 v79, v79
	s_waitcnt lgkmcnt(6)
	v_mfma_f32_32x32x16_bf16 v[96:111], v[212:215], v[130:133], v[96:111]
	v_pk_add_f32 v[230:231], v[230:231], v[76:77]
	v_pk_add_f32 v[230:231], v[230:231], v[78:79]
	v_add_f32_e32 v230, v230, v231
	v_mfma_f32_32x32x16_bf16 v[112:127], v[212:215], v[138:141], 0
	ds_read_b128 v[212:215], v224 offset:6752
	v_add_f32_e32 v191, v191, v230
	v_cvt_pk_bf16_f32 v64, v64, v65
	v_cvt_pk_bf16_f32 v65, v66, v67
	v_cvt_pk_bf16_f32 v66, v68, v69
	s_waitcnt lgkmcnt(6)
	v_mfma_f32_32x32x16_bf16 v[96:111], v[216:219], v[134:137], v[96:111]
	v_cvt_pk_bf16_f32 v67, v70, v71
	v_cvt_pk_bf16_f32 v68, v72, v73
	v_cvt_pk_bf16_f32 v69, v74, v75
	v_mfma_f32_32x32x16_bf16 v[112:127], v[216:219], v[142:145], v[112:127]
	ds_read_b128 v[216:219], v224 offset:6784
	v_cvt_pk_bf16_f32 v70, v76, v77
	v_cvt_pk_bf16_f32 v71, v78, v79
	v_cmp_lt_f32_e32 vcc, s33, v236
	s_cbranch_vccnz .Lat_resc_bE
.Lat_back_bE:
	v_exp_f32_e32 v80, v80
	s_waitcnt lgkmcnt(6)
	v_mfma_f32_32x32x16_bf16 v[96:111], v[220:223], v[146:149], v[96:111]
	v_exp_f32_e32 v81, v81
	v_exp_f32_e32 v82, v82
	v_exp_f32_e32 v83, v83
	v_exp_f32_e32 v84, v84
	v_mfma_f32_32x32x16_bf16 v[112:127], v[220:223], v[154:157], v[112:127]
	ds_read_b128 v[220:223], v224 offset:6816
	v_exp_f32_e32 v85, v85
	v_pk_add_f32 v[230:231], v[80:81], v[82:83]
	v_exp_f32_e32 v86, v86
	s_waitcnt lgkmcnt(2)
	v_mfma_f32_32x32x16_bf16 v[96:111], v[212:215], v[150:153], v[96:111]
	v_exp_f32_e32 v87, v87
	v_pk_add_f32 v[230:231], v[230:231], v[84:85]
	v_exp_f32_e32 v88, v88
	v_exp_f32_e32 v89, v89
	v_mfma_f32_32x32x16_bf16 v[112:127], v[212:215], v[158:161], v[112:127]
	v_pk_add_f32 v[230:231], v[230:231], v[86:87]
	v_exp_f32_e32 v90, v90
	v_exp_f32_e32 v91, v91
	v_pk_add_f32 v[230:231], v[230:231], v[88:89]
	s_waitcnt lgkmcnt(1)
	v_mfma_f32_32x32x16_bf16 v[96:111], v[216:219], v[162:165], v[96:111]
	v_exp_f32_e32 v92, v92
	v_exp_f32_e32 v93, v93
	v_pk_add_f32 v[230:231], v[230:231], v[90:91]
	v_mfma_f32_32x32x16_bf16 v[112:127], v[216:219], v[170:173], v[112:127]
	v_exp_f32_e32 v94, v94
	v_exp_f32_e32 v95, v95
	v_pk_add_f32 v[230:231], v[230:231], v[92:93]
	v_pk_add_f32 v[230:231], v[230:231], v[94:95]
	s_waitcnt lgkmcnt(0)
	v_mfma_f32_32x32x16_bf16 v[96:111], v[220:223], v[166:169], v[96:111]
	v_add_f32_e32 v230, v230, v231
	v_add_f32_e32 v193, v193, v230
	v_cvt_pk_bf16_f32 v80, v80, v81
	v_mfma_f32_32x32x16_bf16 v[112:127], v[220:223], v[174:177], v[112:127]
	v_cvt_pk_bf16_f32 v81, v82, v83
	v_cvt_pk_bf16_f32 v82, v84, v85
	v_cvt_pk_bf16_f32 v83, v86, v87
	v_cvt_pk_bf16_f32 v84, v88, v89
	v_mfma_f32_32x32x16_bf16 v[112:127], v[240:243], v[248:251], v[112:127]
	v_cvt_pk_bf16_f32 v85, v90, v91
	v_cvt_pk_bf16_f32 v86, v92, v93
	v_cvt_pk_bf16_f32 v87, v94, v95
	s_waitcnt vmcnt(0)
	s_barrier
	s_cmpk_gt_u32 s27, 0x81
	s_cbranch_scc1 .Lat_dma_endL
	s_cmp_lt_u32 s27, 2
	s_cselect_b32 s14, s10, s11
	s_add_i32 s14, s14, s24
	s_and_b64 vcc, exec, s[4:5]
	s_cbranch_vccnz .Lat_dmaL_0
	v_mad_u64_u32 v[234:235], s[16:17], v182, s14, v[180:181]
	s_add_i32 m0, s25, s19
	s_nop 0
	global_load_lds_dwordx4 v[234:235], off

; #define LAS __attribute__((address_space(3)))
; __device__ __forceinline__ void attn_unit2(LAS unsigned char* lds, const bf16_t* __restrict__ Q, const bf16_t* __restrict__ KN, const bf16_t* __restrict__ KPE, ...
;     ...
; #pragma unroll
;         for (int st = 0; st < 4; ++st) {
;             const bf16x8 v0 = *(const LAS bf16x8*)(va + st * 32);
;             const bf16x8 v1 = *(const LAS bf16x8*)(va + 32 * VROW + st * 32);
;             const bf16x8 fa = __builtin_bit_cast(bf16x8, pa[st]), fb = __builtin_bit_cast(bf16x8, pb[st]);
;             oa0 = __builtin_amdgcn_mfma_f32_32x32x16_bf16(v0, fa, oa0, 0, 0, 0);
;             oa1 = __builtin_amdgcn_mfma_f32_32x32x16_bf16(v1, fa, oa1, 0, 0, 0);
;             ob0 = __builtin_amdgcn_mfma_f32_32x32x16_bf16(v0, fb, ob0, 0, 0, 0);
;             ob1 = __builtin_amdgcn_mfma_f32_32x32x16_bf16(v1, fb, ob1, 0, 0, 0);
;         }
;         __builtin_amdgcn_sched_barrier(0);
;         __syncthreads();
;         { const int tmp = sc; sc = sn; sn = snn; snn = tmp; }
.Lat_back_aO:
	v_exp_f32_e32 v96, v96
	v_mfma_f32_32x32x16_bf16 v[32:47], v[196:199], v[80:83], v[32:47]
	v_exp_f32_e32 v97, v97
	v_exp_f32_e32 v98, v98
	v_exp_f32_e32 v99, v99
	v_exp_f32_e32 v100, v100
	v_mfma_f32_32x32x16_bf16 v[0:15], v[200:203], v[80:83], v[0:15]
	v_exp_f32_e32 v101, v101
	v_pk_add_f32 v[230:231], v[96:97], v[98:99]
	v_exp_f32_e32 v102, v102
	v_exp_f32_e32 v103, v103
	v_mfma_f32_32x32x16_bf16 v[32:47], v[204:207], v[84:87], v[32:47]
	v_pk_add_f32 v[230:231], v[230:231], v[100:101]
	v_exp_f32_e32 v104, v104
	v_exp_f32_e32 v105, v105
	v_pk_add_f32 v[230:231], v[230:231], v[102:103]
	v_mfma_f32_32x32x16_bf16 v[0:15], v[208:211], v[84:87], v[0:15]
	v_exp_f32_e32 v106, v106
	v_add3_u32 v225, s34, v187, v128
	ds_read_b128 v[196:199], v225 offset:13376
	ds_read_b128 v[200:203], v225 offset:17984
	ds_read_b128 v[204:207], v225 offset:13408
	ds_read_b128 v[208:211], v225 offset:18016
	v_exp_f32_e32 v107, v107
	v_pk_add_f32 v[230:231], v[230:231], v[104:105]
	v_exp_f32_e32 v108, v108
	v_mfma_f32_32x32x16_bf16 v[64:79], v[240:243], v[244:247], 0
	v_exp_f32_e32 v109, v109
	v_pk_add_f32 v[230:231], v[230:231], v[106:107]
	v_exp_f32_e32 v110, v110
	v_exp_f32_e32 v111, v111
	s_waitcnt lgkmcnt(6)
	v_mfma_f32_32x32x16_bf16 v[64:79], v[212:215], v[130:133], v[64:79]
	v_pk_add_f32 v[230:231], v[230:231], v[108:109]
	v_pk_add_f32 v[230:231], v[230:231], v[110:111]
	v_add_f32_e32 v230, v230, v231
	v_mfma_f32_32x32x16_bf16 v[80:95], v[212:215], v[138:141], 0
	ds_read_b128 v[212:215], v224 offset:96
	v_add_f32_e32 v191, v191, v230
	v_cvt_pk_bf16_f32 v96, v96, v97
	v_cvt_pk_bf16_f32 v97, v98, v99
	v_cvt_pk_bf16_f32 v98, v100, v101
	s_waitcnt lgkmcnt(6)
	v_mfma_f32_32x32x16_bf16 v[64:79], v[216:219], v[134:137], v[64:79]
	v_cvt_pk_bf16_f32 v99, v102, v103
	v_cvt_pk_bf16_f32 v100, v104, v105
	v_cvt_pk_bf16_f32 v101, v106, v107
	v_mfma_f32_32x32x16_bf16 v[80:95], v[216:219], v[142:145], v[80:95]
	ds_read_b128 v[216:219], v224 offset:128
	v_cvt_pk_bf16_f32 v102, v108, v109
	v_cvt_pk_bf16_f32 v103, v110, v111
	v_cmp_lt_f32_e32 vcc, s33, v236
	s_cbranch_vccnz .Lat_resc_bO
.Lat_back_bO:
	v_exp_f32_e32 v112, v112
	s_waitcnt lgkmcnt(6)
	v_mfma_f32_32x32x16_bf16 v[64:79], v[220:223], v[146:149], v[64:79]
	v_exp_f32_e32 v113, v113
	v_exp_f32_e32 v114, v114
	v_exp_f32_e32 v115, v115
	v_exp_f32_e32 v116, v116
	v_mfma_f32_32x32x16_bf16 v[80:95], v[220:223], v[154:157], v[80:95]
	ds_read_b128 v[220:223], v224 offset:160
	v_exp_f32_e32 v117, v117
	v_pk_add_f32 v[230:231], v[112:113], v[114:115]
	v_exp_f32_e32 v118, v118
	s_waitcnt lgkmcnt(2)
	v_mfma_f32_32x32x16_bf16 v[64:79], v[212:215], v[150:153], v[64:79]
	v_exp_f32_e32 v119, v119
	v_pk_add_f32 v[230:231], v[230:231], v[116:117]
	v_exp_f32_e32 v120, v120
	v_exp_f32_e32 v121, v121
	v_mfma_f32_32x32x16_bf16 v[80:95], v[212:215], v[158:161], v[80:95]
	v_pk_add_f32 v[230:231], v[230:231], v[118:119]
	v_exp_f32_e32 v122, v122
	v_exp_f32_e32 v123, v123
	v_pk_add_f32 v[230:231], v[230:231], v[120:121]
	s_waitcnt lgkmcnt(1)
	v_mfma_f32_32x32x16_bf16 v[64:79], v[216:219], v[162:165], v[64:79]
	v_exp_f32_e32 v124, v124
	v_exp_f32_e32 v125, v125
	v_pk_add_f32 v[230:231], v[230:231], v[122:123]
	v_mfma_f32_32x32x16_bf16 v[80:95], v[216:219], v[170:173], v[80:95]
	v_exp_f32_e32 v126, v126
	v_exp_f32_e32 v127, v127
	v_pk_add_f32 v[230:231], v[230:231], v[124:125]
	v_pk_add_f32 v[230:231], v[230:231], v[126:127]
	s_waitcnt lgkmcnt(0)
	v_mfma_f32_32x32x16_bf16 v[64:79], v[220:223], v[166:169], v[64:79]
	v_add_f32_e32 v230, v230, v231
	v_add_f32_e32 v193, v193, v230
	v_cvt_pk_bf16_f32 v112, v112, v113
	v_mfma_f32_32x32x16_bf16 v[80:95], v[220:223], v[174:177], v[80:95]
	v_cvt_pk_bf16_f32 v113, v114, v115
	v_cvt_pk_bf16_f32 v114, v116, v117
	v_cvt_pk_bf16_f32 v115, v118, v119
	v_cvt_pk_bf16_f32 v116, v120, v121
	v_mfma_f32_32x32x16_bf16 v[80:95], v[240:243], v[248:251], v[80:95]
	v_cvt_pk_bf16_f32 v117, v122, v123
	v_cvt_pk_bf16_f32 v118, v124, v125
	v_cvt_pk_bf16_f32 v119, v126, v127
	s_add_i32 s27, s27, 1
	s_add_i32 s24, s24, 64
	s_mov_b32 s14, s34
	s_mov_b32 s34, s26
	s_mov_b32 s26, s25
	s_mov_b32 s25, s14
	s_cmpk_lg_i32 s27, 0x84
	s_cbranch_scc1 .Lat_loop
	s_waitcnt lgkmcnt(3)
	v_mfma_f32_32x32x16_bf16 v[16:31], v[196:199], v[96:99], v[16:31]
	s_waitcnt lgkmcnt(2)
	v_mfma_f32_32x32x16_bf16 v[48:63], v[200:203], v[96:99], v[48:63]
	s_waitcnt lgkmcnt(1)
	v_mfma_f32_32x32x16_bf16 v[16:31], v[204:207], v[100:103], v[16:31]
	s_waitcnt lgkmcnt(0)
	v_mfma_f32_32x32x16_bf16 v[48:63], v[208:211], v[100:103], v[48:63]
	v_mfma_f32_32x32x16_bf16 v[32:47], v[196:199], v[112:115], v[32:47]
	v_mfma_f32_32x32x16_bf16 v[0:15], v[200:203], v[112:115], v[0:15]
	v_mfma_f32_32x32x16_bf16 v[32:47], v[204:207], v[116:119], v[32:47]
	v_mfma_f32_32x32x16_bf16 v[0:15], v[208:211], v[116:119], v[0:15]
	s_branch .Lat_done
